# first phase boundary uses the XCD barrier instead of the cooperative-groups grid sync (cg code removed)
# speedup vs baseline: 1.0096x; 1.0064x over previous
; DI unsigned xb_ld(unsigned* p)              { return __hip_atomic_load(p, __ATOMIC_RELAXED, __HIP_MEMORY_SCOPE_AGENT); }
; DI unsigned xb_add(unsigned* p, unsigned v) { return __hip_atomic_fetch_add(p, v, __ATOMIC_RELAXED, __HIP_MEMORY_SCOPE_AGENT); }
; #define XB_SPIN(cond, bar) do { unsigned _sp = 0; while (cond) { __builtin_amdgcn_s_sleep(1); \
;     if ((++_sp & 255u) == 0u) { if (xb_ld(&(bar)[XB_TMO])) break; if (_sp > XB_SPIN_CAP) { atomicAdd(&(bar)[XB_TMO], 1u); break; } } } } while (0)
; DI void xcd_barrier(const XcdBarrier& b) {
;     asm volatile("s_waitcnt vmcnt(0)" ::: "memory");
;     __syncthreads();
;     if (threadIdx.x == 0) {
;         unsigned* bar = b.bar;
;         __builtin_amdgcn_s_waitcnt(0);
;         unsigned nloc = b.st[0], nx = b.st[1];
;         if (nloc == 0u) { xcd_barrier_complete(bar, b.x, nloc, nx); b.st[0] = nloc; b.st[1] = nx; }
;         const unsigned old = xb_add(&bar[XB_XSUB(b.x)], 1u);
;         const unsigned gen = old / nloc;
;         if (old + 1u == (gen + 1u) * nloc) {
;             __builtin_amdgcn_fence(__ATOMIC_RELEASE, "agent");
;             asm volatile("s_waitcnt vmcnt(0)" ::: "memory");
;             const unsigned og = xb_add(&bar[XB_TOP], 1u);
;             const unsigned tg = og / nx;
;             if (og + 1u == (tg + 1u) * nx) xb_add(&bar[XB_TOPGEN], 1u);
;             else XB_SPIN(xb_ld(&bar[XB_TOPGEN]) == tg, bar);
;             __builtin_amdgcn_fence(__ATOMIC_ACQUIRE, "agent");
;             xb_add(&bar[XB_XGEN(b.x)], 1u);
;             asm volatile("s_waitcnt vmcnt(0)" ::: "memory");
;         } else {
;             XB_SPIN(xb_ld(&bar[XB_XGEN(b.x)]) == gen, bar);
;             __builtin_amdgcn_fence(__ATOMIC_ACQUIRE, "agent");
;             asm volatile("s_waitcnt vmcnt(0)" ::: "memory");
;         }
;     }
;     __syncthreads();
; __global__ void __launch_bounds__(NTHREADS, 2) fwd_kernel(Params p_unused) {
;     ...
;         if (ph > ph_lo) { if (ph == ph_lo + 1) grid.sync(); else xcd_barrier(xbar); }
.LBB0_9:
	s_cmp_le_i32 s12, s60
	s_cbranch_scc1 .LBB0_77
	s_cmp_lg_u32 s12, s77
	s_waitcnt lgkmcnt(0)
	s_mov_b64 s[0:1], -1
	s_waitcnt vmcnt(0)
	s_barrier
	s_and_saveexec_b64 s[0:1], s[78:79]
	s_cbranch_execz .LBB0_63
	v_readlane_b32 s2, v254, 63
	s_waitcnt vmcnt(0) expcnt(0) lgkmcnt(0)
	s_nop 0
	v_mov_b32_e32 v0, s2
	ds_read_b32 v3, v0
	v_readlane_b32 s2, v252, 0
	s_waitcnt lgkmcnt(0)
	v_cmp_ne_u32_e32 vcc, 0, v3
	v_mov_b32_e32 v0, s2
	ds_read_b32 v2, v0
	s_cbranch_vccnz .LBB0_27
	s_mov_b32 s2, 1
	s_branch .LBB0_15

; __global__ void __launch_bounds__(NTHREADS, 2) fwd_kernel(Params p_unused) {
;     ...
;         if (ph > ph_lo) { if (ph == ph_lo + 1) grid.sync(); else xcd_barrier(xbar); }
;         PP pp = pk; asm volatile("" : "+s"(pp));
;         if (ph == 0) { const Params p = *pp; phase0(p, lds); continue; }
;         if (ph == NPHASE - 1) { phase_final(pp->out, (const bf16_t*)(pp->ws + WS_HDN), pp->final_g, (const float*)(pp->ws + WS_SSQXP) + (size_t)2 * T * 16); continue; }
;         const int l = (ph - 1) >> 3, s = (ph - 1) & 7;
.LBB0_64:
.LBB0_76:
.LBB0_77:
	s_waitcnt lgkmcnt(0)
	v_readlane_b32 s0, v253, 0
	v_readlane_b32 s1, v253, 1
	s_mov_b64 s[18:19], -1
	s_mov_b64 s[4:5], 0
	s_cmp_lt_i32 s12, 17
	s_mov_b64 s[16:17], 0
	s_cbranch_scc0 .LBB0_81
	s_and_b64 vcc, exec, s[18:19]
	s_cbranch_vccnz .LBB0_87
